# c9_mla_subs_interleaved
# speedup vs baseline: 1.0318x; 1.0008x over previous
.Lfm_odd_exp:
	v_sub_f32_e32 v96, v112, v236
	v_sub_f32_e32 v97, v113, v236
	ds_read_b64_tr_b16 v[112:113], v0 offset:0x200
	v_sub_f32_e32 v98, v114, v236
	v_sub_f32_e32 v99, v115, v236
	ds_read_b64_tr_b16 v[114:115], v0 offset:0xa00
	v_sub_f32_e32 v100, v116, v236
	v_sub_f32_e32 v101, v117, v236
	ds_read_b64_tr_b16 v[116:117], v0 offset:0x1200
	v_sub_f32_e32 v102, v118, v236
	v_sub_f32_e32 v103, v119, v236
	ds_read_b64_tr_b16 v[118:119], v0 offset:0x1a00
	v_sub_f32_e32 v104, v120, v236
	v_sub_f32_e32 v105, v121, v236
	ds_read_b64_tr_b16 v[120:121], v0 offset:0x2200
	v_sub_f32_e32 v106, v122, v236
	v_sub_f32_e32 v107, v123, v236
	ds_read_b64_tr_b16 v[122:123], v0 offset:0x2a00
	v_sub_f32_e32 v108, v124, v236
	v_sub_f32_e32 v109, v125, v236
	ds_read_b64_tr_b16 v[124:125], v0 offset:0x3200
	v_sub_f32_e32 v110, v126, v236
	v_sub_f32_e32 v111, v127, v236
	ds_read_b64_tr_b16 v[126:127], v0 offset:0x3a00
	v_sub_f32_e32 v80, v128, v236
	v_sub_f32_e32 v81, v129, v236
	v_sub_f32_e32 v82, v130, v236
	v_sub_f32_e32 v83, v131, v236
	s_waitcnt lgkmcnt(8)
	v_mfma_f32_32x32x16_bf16 v[64:79], v[192:195], v[208:211], v[64:79]
	v_exp_f32_e32 v96, v96
	v_exp_f32_e32 v80, v80
	v_sub_f32_e32 v84, v132, v236
	v_sub_f32_e32 v85, v133, v236
	v_sub_f32_e32 v86, v134, v236
	v_mfma_f32_32x32x16_bf16 v[64:79], v[10:13], v[204:207], v[64:79]
	v_exp_f32_e32 v97, v97
	v_exp_f32_e32 v81, v81
	v_sub_f32_e32 v87, v135, v236
	v_sub_f32_e32 v88, v136, v236
	v_sub_f32_e32 v89, v137, v236
	v_mfma_f32_32x32x16_bf16 v[64:79], v[6:9], v[200:203], v[64:79]
	v_exp_f32_e32 v98, v98
	v_exp_f32_e32 v82, v82
	v_sub_f32_e32 v90, v138, v236
	v_sub_f32_e32 v91, v139, v236
	v_sub_f32_e32 v92, v140, v236
	v_mfma_f32_32x32x16_bf16 v[64:79], v[2:5], v[196:199], v[64:79]
	v_exp_f32_e32 v99, v99
	v_exp_f32_e32 v83, v83
	v_sub_f32_e32 v93, v141, v236
	v_sub_f32_e32 v94, v142, v236
	v_sub_f32_e32 v95, v143, v236
	ds_read_b64_tr_b16 v[128:129], v0 offset:0x400
	ds_read_b64_tr_b16 v[130:131], v0 offset:0xc00
	ds_read_b64_tr_b16 v[132:133], v0 offset:0x1400
	ds_read_b64_tr_b16 v[134:135], v0 offset:0x1c00
	ds_read_b64_tr_b16 v[136:137], v0 offset:0x2400
	ds_read_b64_tr_b16 v[138:139], v0 offset:0x2c00
	ds_read_b64_tr_b16 v[140:141], v0 offset:0x3400
	ds_read_b64_tr_b16 v[142:143], v0 offset:0x3c00
	s_waitcnt lgkmcnt(8)
	v_mfma_f32_32x32x16_bf16 v[48:63], v[192:195], v[112:115], v[48:63]
	v_exp_f32_e32 v100, v100
	v_exp_f32_e32 v84, v84
	v_mfma_f32_32x32x16_bf16 v[48:63], v[10:13], v[116:119], v[48:63]
	v_exp_f32_e32 v101, v101
	v_exp_f32_e32 v85, v85
	v_mfma_f32_32x32x16_bf16 v[48:63], v[6:9], v[120:123], v[48:63]
	v_exp_f32_e32 v102, v102
	v_exp_f32_e32 v86, v86
	v_mfma_f32_32x32x16_bf16 v[48:63], v[2:5], v[124:127], v[48:63]
	v_exp_f32_e32 v103, v103
	v_exp_f32_e32 v87, v87
	ds_read_b64_tr_b16 v[112:113], v0 offset:0x600
	ds_read_b64_tr_b16 v[114:115], v0 offset:0xe00
	ds_read_b64_tr_b16 v[116:117], v0 offset:0x1600
	ds_read_b64_tr_b16 v[118:119], v0 offset:0x1e00
	ds_read_b64_tr_b16 v[120:121], v0 offset:0x2600
	ds_read_b64_tr_b16 v[122:123], v0 offset:0x2e00
	ds_read_b64_tr_b16 v[124:125], v0 offset:0x3600
	ds_read_b64_tr_b16 v[126:127], v0 offset:0x3e00
	s_waitcnt lgkmcnt(8)
	v_mfma_f32_32x32x16_bf16 v[32:47], v[192:195], v[128:131], v[32:47]
	v_exp_f32_e32 v104, v104
	v_exp_f32_e32 v88, v88
	v_mfma_f32_32x32x16_bf16 v[32:47], v[10:13], v[132:135], v[32:47]
	v_exp_f32_e32 v105, v105
	v_exp_f32_e32 v89, v89
	v_mfma_f32_32x32x16_bf16 v[32:47], v[6:9], v[136:139], v[32:47]
	v_exp_f32_e32 v106, v106
	v_exp_f32_e32 v90, v90
	v_mfma_f32_32x32x16_bf16 v[32:47], v[2:5], v[140:143], v[32:47]
	v_exp_f32_e32 v107, v107
	v_exp_f32_e32 v91, v91
	s_waitcnt lgkmcnt(0)
	v_mfma_f32_32x32x16_bf16 v[16:31], v[192:195], v[112:115], v[16:31]
	v_exp_f32_e32 v108, v108
	v_exp_f32_e32 v92, v92
	v_mfma_f32_32x32x16_bf16 v[16:31], v[10:13], v[116:119], v[16:31]
	v_exp_f32_e32 v109, v109
	v_exp_f32_e32 v93, v93
	v_mfma_f32_32x32x16_bf16 v[16:31], v[6:9], v[120:123], v[16:31]
	v_exp_f32_e32 v110, v110
	v_exp_f32_e32 v94, v94
	v_mfma_f32_32x32x16_bf16 v[16:31], v[2:5], v[124:127], v[16:31]
	v_exp_f32_e32 v111, v111
	v_exp_f32_e32 v95, v95
	s_branch .Lresc_mla_odd

.Lfm_even_exp:
	v_sub_f32_e32 v96, v112, v236
	v_sub_f32_e32 v97, v113, v236
	ds_read_b64_tr_b16 v[112:113], v243 offset:0x200
	v_sub_f32_e32 v98, v114, v236
	v_sub_f32_e32 v99, v115, v236
	ds_read_b64_tr_b16 v[114:115], v243 offset:0xa00
	v_sub_f32_e32 v100, v116, v236
	v_sub_f32_e32 v101, v117, v236
	ds_read_b64_tr_b16 v[116:117], v243 offset:0x1200
	v_sub_f32_e32 v102, v118, v236
	v_sub_f32_e32 v103, v119, v236
	ds_read_b64_tr_b16 v[118:119], v243 offset:0x1a00
	v_sub_f32_e32 v104, v120, v236
	v_sub_f32_e32 v105, v121, v236
	ds_read_b64_tr_b16 v[120:121], v243 offset:0x2200
	v_sub_f32_e32 v106, v122, v236
	v_sub_f32_e32 v107, v123, v236
	ds_read_b64_tr_b16 v[122:123], v243 offset:0x2a00
	v_sub_f32_e32 v108, v124, v236
	v_sub_f32_e32 v109, v125, v236
	ds_read_b64_tr_b16 v[124:125], v243 offset:0x3200
	v_sub_f32_e32 v110, v126, v236
	v_sub_f32_e32 v111, v127, v236
	ds_read_b64_tr_b16 v[126:127], v243 offset:0x3a00
	v_sub_f32_e32 v80, v128, v236
	v_sub_f32_e32 v81, v129, v236
	v_sub_f32_e32 v82, v130, v236
	v_sub_f32_e32 v83, v131, v236
	s_waitcnt lgkmcnt(8)
	v_mfma_f32_32x32x16_bf16 v[64:79], v[192:195], v[208:211], v[64:79]
	v_exp_f32_e32 v96, v96
	v_exp_f32_e32 v80, v80
	v_sub_f32_e32 v84, v132, v236
	v_sub_f32_e32 v85, v133, v236
	v_sub_f32_e32 v86, v134, v236
	v_mfma_f32_32x32x16_bf16 v[64:79], v[10:13], v[204:207], v[64:79]
	v_exp_f32_e32 v97, v97
	v_exp_f32_e32 v81, v81
	v_sub_f32_e32 v87, v135, v236
	v_sub_f32_e32 v88, v136, v236
	v_sub_f32_e32 v89, v137, v236
	v_mfma_f32_32x32x16_bf16 v[64:79], v[6:9], v[200:203], v[64:79]
	v_exp_f32_e32 v98, v98
	v_exp_f32_e32 v82, v82
	v_sub_f32_e32 v90, v138, v236
	v_sub_f32_e32 v91, v139, v236
	v_sub_f32_e32 v92, v140, v236
	v_mfma_f32_32x32x16_bf16 v[64:79], v[2:5], v[196:199], v[64:79]
	v_exp_f32_e32 v99, v99
	v_exp_f32_e32 v83, v83
	v_sub_f32_e32 v93, v141, v236
	v_sub_f32_e32 v94, v142, v236
	v_sub_f32_e32 v95, v143, v236
	ds_read_b64_tr_b16 v[128:129], v243 offset:0x400
	ds_read_b64_tr_b16 v[130:131], v243 offset:0xc00
	ds_read_b64_tr_b16 v[132:133], v243 offset:0x1400
	ds_read_b64_tr_b16 v[134:135], v243 offset:0x1c00
	ds_read_b64_tr_b16 v[136:137], v243 offset:0x2400
	ds_read_b64_tr_b16 v[138:139], v243 offset:0x2c00
	ds_read_b64_tr_b16 v[140:141], v243 offset:0x3400
	ds_read_b64_tr_b16 v[142:143], v243 offset:0x3c00
	s_waitcnt lgkmcnt(8)
	v_mfma_f32_32x32x16_bf16 v[48:63], v[192:195], v[112:115], v[48:63]
	v_exp_f32_e32 v100, v100
	v_exp_f32_e32 v84, v84
	v_mfma_f32_32x32x16_bf16 v[48:63], v[10:13], v[116:119], v[48:63]
	v_exp_f32_e32 v101, v101
	v_exp_f32_e32 v85, v85
	v_mfma_f32_32x32x16_bf16 v[48:63], v[6:9], v[120:123], v[48:63]
	v_exp_f32_e32 v102, v102
	v_exp_f32_e32 v86, v86
	v_mfma_f32_32x32x16_bf16 v[48:63], v[2:5], v[124:127], v[48:63]
	v_exp_f32_e32 v103, v103
	v_exp_f32_e32 v87, v87
	ds_read_b64_tr_b16 v[112:113], v243 offset:0x600
	ds_read_b64_tr_b16 v[114:115], v243 offset:0xe00
	ds_read_b64_tr_b16 v[116:117], v243 offset:0x1600
	ds_read_b64_tr_b16 v[118:119], v243 offset:0x1e00
	ds_read_b64_tr_b16 v[120:121], v243 offset:0x2600
	ds_read_b64_tr_b16 v[122:123], v243 offset:0x2e00
	ds_read_b64_tr_b16 v[124:125], v243 offset:0x3600
	ds_read_b64_tr_b16 v[126:127], v243 offset:0x3e00
	s_waitcnt lgkmcnt(8)
	v_mfma_f32_32x32x16_bf16 v[32:47], v[192:195], v[128:131], v[32:47]
	v_exp_f32_e32 v104, v104
	v_exp_f32_e32 v88, v88
	v_mfma_f32_32x32x16_bf16 v[32:47], v[10:13], v[132:135], v[32:47]
	v_exp_f32_e32 v105, v105
	v_exp_f32_e32 v89, v89
	v_mfma_f32_32x32x16_bf16 v[32:47], v[6:9], v[136:139], v[32:47]
	v_exp_f32_e32 v106, v106
	v_exp_f32_e32 v90, v90
	v_mfma_f32_32x32x16_bf16 v[32:47], v[2:5], v[140:143], v[32:47]
	v_exp_f32_e32 v107, v107
	v_exp_f32_e32 v91, v91
	s_waitcnt lgkmcnt(0)
	v_mfma_f32_32x32x16_bf16 v[16:31], v[192:195], v[112:115], v[16:31]
	v_exp_f32_e32 v108, v108
	v_exp_f32_e32 v92, v92
	v_mfma_f32_32x32x16_bf16 v[16:31], v[10:13], v[116:119], v[16:31]
	v_exp_f32_e32 v109, v109
	v_exp_f32_e32 v93, v93
	v_mfma_f32_32x32x16_bf16 v[16:31], v[6:9], v[120:123], v[16:31]
	v_exp_f32_e32 v110, v110
	v_exp_f32_e32 v94, v94
	v_mfma_f32_32x32x16_bf16 v[16:31], v[2:5], v[124:127], v[16:31]
	v_exp_f32_e32 v111, v111
	v_exp_f32_e32 v95, v95
	s_branch .Lresc_mla_even
